# phase-0 input-row conversion: all 8 row loads in flight with counted vmcnt(7) waits (was 8 serial load/wait(0)/store rounds per row); on top of v17
# baseline (speedup 1.0000x reference)
.LBB0_25:
	v_add_u32_e32 v2, 0xffffe000, v1
	v_cmp_lt_i32_e64 s[0:1], s16, v1
	v_readlane_b32 s36, v250, 0
	v_readlane_b32 s50, v250, 14
	v_cndmask_b32_e64 v8, v1, v2, s[0:1]
	v_ashrrev_i32_e32 v9, 31, v8
	v_cndmask_b32_e64 v23, v18, v19, s[0:1]
	s_waitcnt lgkmcnt(0)
	v_cndmask_b32_e64 v22, v20, v21, s[0:1]
	v_lshlrev_b64 v[24:25], 13, v[8:9]
	v_lshl_add_u64 v[22:23], v[22:23], 0, v[24:25]
	v_lshl_add_u64 v[36:37], v[22:23], 0, v[4:5]
	v_add_co_u32_e64 v36, s[4:5], s17, v36
	s_nop 1
	v_addc_co_u32_e64 v37, s[4:5], 0, v37, s[4:5]
	global_load_dwordx4 v[64:67], v[36:37], off offset:-4096
	global_load_dwordx4 v[68:71], v[36:37], off offset:-3072
	global_load_dwordx4 v[72:75], v[36:37], off offset:-2048
	global_load_dwordx4 v[76:79], v[36:37], off offset:-1024
	global_load_dwordx4 v[80:83], v[36:37], off
	global_load_dwordx4 v[84:87], v[36:37], off offset:1024
	global_load_dwordx4 v[88:91], v[36:37], off offset:2048
	global_load_dwordx4 v[92:95], v[36:37], off offset:3072
	v_cndmask_b32_e64 v2, v16, v17, s[0:1]
	v_readlane_b32 s51, v250, 15
	v_lshlrev_b64 v[28:29], 12, v[8:9]
	v_readlane_b32 s37, v250, 1
	v_lshl_add_u64 v[26:27], s[50:51], 0, v[2:3]
	v_lshl_add_u64 v[26:27], v[26:27], 0, v[28:29]
	v_lshl_add_u64 v[60:61], v[26:27], 0, v[6:7]
	v_readlane_b32 s38, v250, 2
	v_readlane_b32 s39, v250, 3
	v_readlane_b32 s40, v250, 4
	v_readlane_b32 s41, v250, 5
	v_readlane_b32 s42, v250, 6
	v_readlane_b32 s43, v250, 7
	v_readlane_b32 s44, v250, 8
	v_readlane_b32 s45, v250, 9
	v_readlane_b32 s46, v250, 10
	v_readlane_b32 s47, v250, 11
	v_readlane_b32 s48, v250, 12
	v_readlane_b32 s49, v250, 13
	s_waitcnt vmcnt(7)
	v_cvt_pk_bf16_f32 v26, v64, v65
	v_cvt_pk_bf16_f32 v27, v66, v67
	global_store_dwordx2 v[60:61], v[26:27], off
	v_mul_f32_e32 v2, v65, v65
	v_mul_f32_e32 v23, v67, v67
	v_fmac_f32_e32 v2, v64, v64
	v_fmac_f32_e32 v23, v66, v66
	v_add_f32_e32 v2, v2, v23
	s_waitcnt vmcnt(7)
	v_cvt_pk_bf16_f32 v30, v68, v69
	v_cvt_pk_bf16_f32 v31, v70, v71
	global_store_dwordx2 v[60:61], v[30:31], off offset:512
	v_mul_f32_e32 v22, v69, v69
	v_mul_f32_e32 v23, v71, v71
	v_fmac_f32_e32 v22, v68, v68
	v_fmac_f32_e32 v23, v70, v70
	v_add_f32_e32 v22, v22, v23
	v_add_f32_e32 v2, v2, v22
	s_waitcnt vmcnt(7)
	v_cvt_pk_bf16_f32 v26, v72, v73
	v_cvt_pk_bf16_f32 v27, v74, v75
	global_store_dwordx2 v[60:61], v[26:27], off offset:1024
	v_mul_f32_e32 v22, v73, v73
	v_mul_f32_e32 v23, v75, v75
	v_fmac_f32_e32 v22, v72, v72
	v_fmac_f32_e32 v23, v74, v74
	v_add_f32_e32 v22, v22, v23
	v_add_f32_e32 v2, v2, v22
	s_waitcnt vmcnt(7)
	v_cvt_pk_bf16_f32 v30, v76, v77
	v_cvt_pk_bf16_f32 v31, v78, v79
	global_store_dwordx2 v[60:61], v[30:31], off offset:1536
	v_mul_f32_e32 v22, v77, v77
	v_mul_f32_e32 v23, v79, v79
	v_fmac_f32_e32 v22, v76, v76
	v_fmac_f32_e32 v23, v78, v78
	v_add_f32_e32 v22, v22, v23
	v_add_f32_e32 v2, v2, v22
	s_waitcnt vmcnt(7)
	v_cvt_pk_bf16_f32 v26, v80, v81
	v_cvt_pk_bf16_f32 v27, v82, v83
	global_store_dwordx2 v[60:61], v[26:27], off offset:2048
	v_mul_f32_e32 v22, v81, v81
	v_mul_f32_e32 v23, v83, v83
	v_fmac_f32_e32 v22, v80, v80
	v_fmac_f32_e32 v23, v82, v82
	v_add_f32_e32 v22, v22, v23
	v_add_f32_e32 v2, v2, v22
	s_waitcnt vmcnt(7)
	v_cvt_pk_bf16_f32 v30, v84, v85
	v_cvt_pk_bf16_f32 v31, v86, v87
	global_store_dwordx2 v[60:61], v[30:31], off offset:2560
	v_mul_f32_e32 v22, v85, v85
	v_mul_f32_e32 v23, v87, v87
	v_fmac_f32_e32 v22, v84, v84
	v_fmac_f32_e32 v23, v86, v86
	v_add_f32_e32 v22, v22, v23
	v_add_f32_e32 v2, v2, v22
	s_waitcnt vmcnt(7)
	v_cvt_pk_bf16_f32 v26, v88, v89
	v_cvt_pk_bf16_f32 v27, v90, v91
	global_store_dwordx2 v[60:61], v[26:27], off offset:3072
	v_mul_f32_e32 v22, v89, v89
	v_mul_f32_e32 v23, v91, v91
	v_fmac_f32_e32 v22, v88, v88
	v_fmac_f32_e32 v23, v90, v90
	v_add_f32_e32 v22, v22, v23
	v_add_f32_e32 v2, v2, v22
	s_waitcnt vmcnt(7)
	v_cvt_pk_bf16_f32 v30, v92, v93
	v_cvt_pk_bf16_f32 v31, v94, v95
	global_store_dwordx2 v[60:61], v[30:31], off offset:3584
	v_mul_f32_e32 v22, v93, v93
	v_mul_f32_e32 v23, v95, v95
	v_fmac_f32_e32 v22, v92, v92
	v_fmac_f32_e32 v23, v94, v94
	v_add_f32_e32 v22, v22, v23
	v_add_f32_e32 v2, v2, v22
	ds_bpermute_b32 v22, v10, v2
	s_waitcnt lgkmcnt(0)
	v_add_f32_e32 v2, v2, v22
	ds_bpermute_b32 v22, v11, v2
	s_waitcnt lgkmcnt(0)
	v_add_f32_e32 v2, v2, v22
	ds_bpermute_b32 v22, v12, v2
	s_waitcnt lgkmcnt(0)
	v_add_f32_e32 v2, v2, v22
	ds_bpermute_b32 v22, v13, v2
	s_waitcnt lgkmcnt(0)
	v_add_f32_e32 v2, v2, v22
	ds_bpermute_b32 v22, v14, v2
	s_waitcnt lgkmcnt(0)
	v_add_f32_e32 v2, v2, v22
	ds_bpermute_b32 v22, v15, v2
	s_and_saveexec_b64 s[4:5], vcc
	s_cbranch_execz .LBB0_24
	s_waitcnt lgkmcnt(0)
	v_add_f32_e32 v2, v2, v22
	v_fma_f32 v2, v2, s18, 0.5
	v_trunc_f32_e32 v2, v2
	v_mul_f32_e32 v22, 0x2f800000, v2
	v_floor_f32_e32 v22, v22
	v_mov_b32_e32 v23, s14
	v_mov_b32_e32 v24, s9
	v_fmac_f32_e32 v2, 0xcf800000, v22
	v_cndmask_b32_e64 v23, v23, v24, s[0:1]
	v_cvt_u32_f32_e32 v24, v2
	v_cvt_u32_f32_e32 v25, v22
	v_mov_b32_e32 v26, s13
	v_mov_b32_e32 v2, s8
	v_cndmask_b32_e64 v22, v26, v2, s[0:1]
	v_lshl_add_u64 v[8:9], v[8:9], 3, v[22:23]
	global_store_dwordx2 v[8:9], v[24:25], off
	s_branch .LBB0_24
